# v54 + attention loop: the four K-address VALU adds moved from the segment head (right after the barrier) to after the 4th P.V MFMA (6.4 start-of-segment VALU)
# speedup vs baseline: 1.0029x; 1.0029x over previous
.Lat_loop:
	s_cmp_ge_i32 s5, s81
	s_cbranch_scc1 .Lat_rare_8
	s_waitcnt lgkmcnt(8)
	v_mfma_f32_32x32x16_bf16 v[0:15], v[224:227], v[114:117], v[0:15]
	v_exp_f32_e32 v82, v82
	v_exp_f32_e32 v83, v83
	ds_read_b64_tr_b16 v[224:225], v215 offset:8192
	ds_read_b64_tr_b16 v[226:227], v215 offset:10240
	v_mfma_f32_32x32x16_bf16 v[16:31], v[228:231], v[114:117], v[16:31]
	v_exp_f32_e32 v84, v84
	v_exp_f32_e32 v85, v85
	v_add_f32_e32 v180, v82, v83
	ds_read_b64_tr_b16 v[228:229], v165 offset:8192
	ds_read_b64_tr_b16 v[230:231], v165 offset:10240
	v_mfma_f32_32x32x16_bf16 v[32:47], v[232:235], v[114:117], v[32:47]
	v_exp_f32_e32 v86, v86
	v_exp_f32_e32 v87, v87
	v_add_f32_e32 v180, v180, v84
	v_add_f32_e32 v180, v180, v85
	ds_read_b64_tr_b16 v[232:233], v216 offset:8192
	ds_read_b64_tr_b16 v[234:235], v216 offset:10240
	v_mfma_f32_32x32x16_bf16 v[48:63], v[236:239], v[114:117], v[48:63]
	v_add_u32_e32 v188, s12, v157
	v_add_u32_e32 v189, s12, v158
	v_add_u32_e32 v222, s12, v159
	v_add_u32_e32 v223, s12, v160
	v_exp_f32_e32 v88, v88
	v_exp_f32_e32 v89, v89
	v_add_f32_e32 v180, v180, v86
	v_add_f32_e32 v180, v180, v87
	ds_read_b64_tr_b16 v[236:237], v217 offset:8192
	ds_read_b64_tr_b16 v[238:239], v217 offset:10240
	s_waitcnt lgkmcnt(8)
	v_mfma_f32_32x32x16_bf16 v[0:15], v[240:243], v[118:121], v[0:15]
	v_exp_f32_e32 v90, v90
	v_exp_f32_e32 v91, v91
	v_add_f32_e32 v180, v180, v88
	v_cvt_pk_bf16_f32 v114, v82, v83
	ds_read_b64_tr_b16 v[240:241], v215 offset:12288
	ds_read_b64_tr_b16 v[242:243], v215 offset:14336
	v_mfma_f32_32x32x16_bf16 v[16:31], v[130:133], v[118:121], v[16:31]
	v_exp_f32_e32 v92, v92
	v_exp_f32_e32 v93, v93
	v_add_f32_e32 v180, v180, v89
	v_cvt_pk_bf16_f32 v115, v84, v85
	ds_read_b64_tr_b16 v[130:131], v165 offset:12288
	ds_read_b64_tr_b16 v[132:133], v165 offset:14336
	v_mfma_f32_32x32x16_bf16 v[32:47], v[134:137], v[118:121], v[32:47]
	v_exp_f32_e32 v94, v94
	v_exp_f32_e32 v95, v95
	v_add_f32_e32 v180, v180, v90
	v_cvt_pk_bf16_f32 v116, v86, v87
	ds_read_b64_tr_b16 v[134:135], v216 offset:12288
	ds_read_b64_tr_b16 v[136:137], v216 offset:14336
	v_mfma_f32_32x32x16_bf16 v[48:63], v[184:187], v[118:121], v[48:63]
	v_exp_f32_e32 v96, v96
	v_exp_f32_e32 v97, v97
	v_add_f32_e32 v180, v180, v91
	v_cvt_pk_bf16_f32 v117, v88, v89
	ds_read_b64_tr_b16 v[184:185], v217 offset:12288
	ds_read_b64_tr_b16 v[186:187], v217 offset:14336
	s_waitcnt lgkmcnt(8)
	v_mfma_f32_32x32x16_bf16 v[0:15], v[224:227], v[122:125], v[0:15]
	v_exp_f32_e32 v98, v98
	v_exp_f32_e32 v99, v99
	v_add_f32_e32 v180, v180, v92
	v_cvt_pk_bf16_f32 v118, v90, v91
	v_mfma_f32_32x32x16_bf16 v[16:31], v[228:231], v[122:125], v[16:31]
	v_exp_f32_e32 v100, v100
	v_exp_f32_e32 v101, v101
	v_add_f32_e32 v180, v180, v93
	v_cvt_pk_bf16_f32 v119, v92, v93
	v_mfma_f32_32x32x16_bf16 v[32:47], v[232:235], v[122:125], v[32:47]
	v_exp_f32_e32 v102, v102
	v_exp_f32_e32 v103, v103
	v_add_f32_e32 v180, v180, v94
	v_cvt_pk_bf16_f32 v120, v94, v95
	v_mfma_f32_32x32x16_bf16 v[48:63], v[236:239], v[122:125], v[48:63]
	v_exp_f32_e32 v104, v104
	v_exp_f32_e32 v105, v105
	v_add_f32_e32 v180, v180, v95
	v_cvt_pk_bf16_f32 v121, v96, v97
	ds_read_b128 v[224:227], v188
	ds_read_b128 v[228:231], v189
	ds_read_b128 v[232:235], v222
	ds_read_b128 v[236:239], v223
	s_waitcnt lgkmcnt(4)
	v_mfma_f32_32x32x16_bf16 v[0:15], v[240:243], v[126:129], v[0:15]
	v_exp_f32_e32 v106, v106
	v_exp_f32_e32 v107, v107
	v_add_f32_e32 v180, v180, v96
	v_add_f32_e32 v180, v180, v97
	v_mfma_f32_32x32x16_bf16 v[16:31], v[130:133], v[126:129], v[16:31]
	v_exp_f32_e32 v108, v108
	v_exp_f32_e32 v109, v109
	v_add_f32_e32 v180, v180, v98
	v_add_f32_e32 v180, v180, v99
	v_mfma_f32_32x32x16_bf16 v[32:47], v[134:137], v[126:129], v[32:47]
	v_exp_f32_e32 v110, v110
	v_exp_f32_e32 v111, v111
	v_add_f32_e32 v180, v180, v100
	v_add_f32_e32 v180, v180, v101
	v_mfma_f32_32x32x16_bf16 v[48:63], v[184:187], v[126:129], v[48:63]
	v_exp_f32_e32 v112, v112
	v_exp_f32_e32 v113, v113
	v_add_f32_e32 v180, v180, v102
	v_add_f32_e32 v180, v180, v103
	ds_read_b128 v[240:243], v188 offset:4096
	ds_read_b128 v[130:133], v189 offset:4096
	ds_read_b128 v[134:137], v222 offset:4096
	ds_read_b128 v[184:187], v223 offset:4096
	s_waitcnt lgkmcnt(4)
	v_mfma_f32_32x32x16_bf16 v[82:97], v[224:227], v[150:153], v[64:79]
	v_add_f32_e32 v180, v180, v104
	v_add_f32_e32 v180, v180, v105
	v_add_f32_e32 v180, v180, v106
	v_cvt_pk_bf16_f32 v122, v98, v99
	v_cvt_pk_bf16_f32 v123, v100, v101
	s_add_i32 m0, s13, s68
	s_nop 0
	global_load_lds_dwordx4 v154, s[14:15]
	v_mfma_f32_32x32x16_bf16 v[82:97], v[228:231], v[146:149], v[82:97]
	v_add_f32_e32 v180, v180, v107
	v_add_f32_e32 v180, v180, v108
	v_add_f32_e32 v180, v180, v109
	v_cvt_pk_bf16_f32 v124, v102, v103
	v_cvt_pk_bf16_f32 v125, v104, v105
	s_add_i32 m0, s17, s69
	s_nop 0
	global_load_lds_dwordx4 v155, s[18:19]
	v_mfma_f32_32x32x16_bf16 v[82:97], v[232:235], v[142:145], v[82:97]
	v_add_f32_e32 v180, v180, v110
	v_add_f32_e32 v180, v180, v111
	v_cvt_pk_bf16_f32 v126, v106, v107
	v_cvt_pk_bf16_f32 v127, v108, v109
	s_add_i32 m0, m0, 0x400
	s_nop 0
	global_load_lds_dwordx4 v156, s[18:19]
	v_mfma_f32_32x32x16_bf16 v[82:97], v[236:239], v[138:141], v[82:97]
	v_add_f32_e32 v180, v180, v112
	v_add_f32_e32 v180, v180, v113
	v_cvt_pk_bf16_f32 v128, v110, v111
	v_cvt_pk_bf16_f32 v129, v112, v113
	v_cmp_ngt_f32_e32 vcc, s23, v180
	s_add_i32 s12, s12, 8192
	s_cmp_eq_u32 s12, 32768
	s_cselect_b32 s12, 0, s12
	s_add_i32 s84, s84, 16384
	s_cmp_eq_u32 s84, 114688
	s_cselect_b32 s84, 32768, s84
	s_waitcnt lgkmcnt(0)
	v_mfma_f32_32x32x16_bf16 v[98:113], v[240:243], v[150:153], v[64:79]
	v_add_u32_e32 v215, s84, v161
	v_add_u32_e32 v165, s84, v162
	v_add_u32_e32 v216, s84, v163
	v_add_u32_e32 v217, s84, v164
	ds_read_b64_tr_b16 v[224:225], v215 offset:0
	ds_read_b64_tr_b16 v[226:227], v215 offset:2048
	s_add_i32 s13, s13, 8192
	s_cmp_eq_u32 s13, 32768
	s_cselect_b32 s13, 0, s13
	v_mfma_f32_32x32x16_bf16 v[98:113], v[130:133], v[146:149], v[98:113]
	ds_read_b64_tr_b16 v[228:229], v165 offset:0
	ds_read_b64_tr_b16 v[230:231], v165 offset:2048
	ds_read_b64_tr_b16 v[232:233], v216 offset:0
	ds_read_b64_tr_b16 v[234:235], v216 offset:2048
	s_add_i32 s17, s17, 16384
	s_cmp_eq_u32 s17, 114688
	s_cselect_b32 s17, 32768, s17
	v_mfma_f32_32x32x16_bf16 v[98:113], v[134:137], v[142:145], v[98:113]
	ds_read_b64_tr_b16 v[236:237], v217 offset:0
	ds_read_b64_tr_b16 v[238:239], v217 offset:2048
	s_add_i32 s85, s85, 1
	s_cmp_lt_u32 s85, s6
	s_cselect_b32 s8, 0x40000, 0
	v_mfma_f32_32x32x16_bf16 v[98:113], v[184:187], v[138:141], v[98:113]
	s_add_u32 s14, s14, s8
	s_addc_u32 s15, s15, 0
	s_add_u32 s18, s18, s8
	s_addc_u32 s19, s19, 0
	ds_read_b64_tr_b16 v[240:241], v215 offset:4096
	ds_read_b64_tr_b16 v[242:243], v215 offset:6144
	ds_read_b64_tr_b16 v[130:131], v165 offset:4096
	ds_read_b64_tr_b16 v[132:133], v165 offset:6144
	ds_read_b64_tr_b16 v[134:135], v216 offset:4096
	ds_read_b64_tr_b16 v[136:137], v216 offset:6144
	ds_read_b64_tr_b16 v[184:185], v217 offset:4096
	ds_read_b64_tr_b16 v[186:187], v217 offset:6144
	s_cbranch_vccz .Lat_norescale_9
	ds_bpermute_b32 v182, v214, v180
	s_waitcnt lgkmcnt(0)
	v_add_f32_e32 v182, v180, v182
	v_min_f32_e32 v182, 0x7f61b1e6, v182
	v_log_f32_e32 v182, v182
	s_nop 0
	v_floor_f32_e32 v182, v182
	v_max_f32_e32 v182, 0, v182
	v_exp_f32_e64 v183, -v182
	v_add_f32_e32 v80, v80, v182
	v_mul_f32_e32 v81, v81, v183
	v_mul_f32_e32 v180, v180, v183
	v_xor_b32_e32 v64, 0x80000000, v80
	v_mov_b32_e32 v65, v64
	v_mov_b32_e32 v66, v64
	v_mov_b32_e32 v67, v64
	v_mov_b32_e32 v68, v64
	v_mov_b32_e32 v69, v64
	v_mov_b32_e32 v70, v64
	v_mov_b32_e32 v71, v64
	v_mov_b32_e32 v72, v64
	v_mov_b32_e32 v73, v64
	v_mov_b32_e32 v74, v64
	v_mov_b32_e32 v75, v64
	v_mov_b32_e32 v76, v64
	v_mov_b32_e32 v77, v64
	v_mov_b32_e32 v78, v64
	v_mov_b32_e32 v79, v64
	v_sub_f32_e32 v82, v82, v182
	v_sub_f32_e32 v83, v83, v182
	v_sub_f32_e32 v84, v84, v182
	v_sub_f32_e32 v85, v85, v182
	v_sub_f32_e32 v86, v86, v182
	v_sub_f32_e32 v87, v87, v182
	v_sub_f32_e32 v88, v88, v182
	v_sub_f32_e32 v89, v89, v182
	v_sub_f32_e32 v90, v90, v182
	v_sub_f32_e32 v91, v91, v182
	v_sub_f32_e32 v92, v92, v182
	v_sub_f32_e32 v93, v93, v182
	v_sub_f32_e32 v94, v94, v182
	v_sub_f32_e32 v95, v95, v182
	v_sub_f32_e32 v96, v96, v182
	v_sub_f32_e32 v97, v97, v182
	v_sub_f32_e32 v98, v98, v182
	v_sub_f32_e32 v99, v99, v182
	v_sub_f32_e32 v100, v100, v182
	v_sub_f32_e32 v101, v101, v182
	v_sub_f32_e32 v102, v102, v182
	v_sub_f32_e32 v103, v103, v182
	v_sub_f32_e32 v104, v104, v182
	v_sub_f32_e32 v105, v105, v182
	v_sub_f32_e32 v106, v106, v182
	v_sub_f32_e32 v107, v107, v182
	v_sub_f32_e32 v108, v108, v182
	v_sub_f32_e32 v109, v109, v182
	v_sub_f32_e32 v110, v110, v182
	v_sub_f32_e32 v111, v111, v182
	v_sub_f32_e32 v112, v112, v182
	v_sub_f32_e32 v113, v113, v182
	v_mul_f32_e32 v0, v0, v183
	v_mul_f32_e32 v1, v1, v183
	v_mul_f32_e32 v2, v2, v183
	v_mul_f32_e32 v3, v3, v183
	v_mul_f32_e32 v4, v4, v183
	v_mul_f32_e32 v5, v5, v183
	v_mul_f32_e32 v6, v6, v183
	v_mul_f32_e32 v7, v7, v183
	v_mul_f32_e32 v8, v8, v183
	v_mul_f32_e32 v9, v9, v183
	v_mul_f32_e32 v10, v10, v183
	v_mul_f32_e32 v11, v11, v183
	v_mul_f32_e32 v12, v12, v183
	v_mul_f32_e32 v13, v13, v183
	v_mul_f32_e32 v14, v14, v183
	v_mul_f32_e32 v15, v15, v183
	v_mul_f32_e32 v16, v16, v183
	v_mul_f32_e32 v17, v17, v183
	v_mul_f32_e32 v18, v18, v183
	v_mul_f32_e32 v19, v19, v183
	v_mul_f32_e32 v20, v20, v183
	v_mul_f32_e32 v21, v21, v183
	v_mul_f32_e32 v22, v22, v183
	v_mul_f32_e32 v23, v23, v183
	v_mul_f32_e32 v24, v24, v183
	v_mul_f32_e32 v25, v25, v183
	v_mul_f32_e32 v26, v26, v183
	v_mul_f32_e32 v27, v27, v183
	v_mul_f32_e32 v28, v28, v183
	v_mul_f32_e32 v29, v29, v183
	v_mul_f32_e32 v30, v30, v183
	v_mul_f32_e32 v31, v31, v183
	v_mul_f32_e32 v32, v32, v183
	v_mul_f32_e32 v33, v33, v183
	v_mul_f32_e32 v34, v34, v183
	v_mul_f32_e32 v35, v35, v183
	v_mul_f32_e32 v36, v36, v183
	v_mul_f32_e32 v37, v37, v183
	v_mul_f32_e32 v38, v38, v183
	v_mul_f32_e32 v39, v39, v183
	v_mul_f32_e32 v40, v40, v183
	v_mul_f32_e32 v41, v41, v183
	v_mul_f32_e32 v42, v42, v183
	v_mul_f32_e32 v43, v43, v183
	v_mul_f32_e32 v44, v44, v183
	v_mul_f32_e32 v45, v45, v183
	v_mul_f32_e32 v46, v46, v183
	v_mul_f32_e32 v47, v47, v183
	v_mul_f32_e32 v48, v48, v183
	v_mul_f32_e32 v49, v49, v183
	v_mul_f32_e32 v50, v50, v183
	v_mul_f32_e32 v51, v51, v183
	v_mul_f32_e32 v52, v52, v183
	v_mul_f32_e32 v53, v53, v183
	v_mul_f32_e32 v54, v54, v183
	v_mul_f32_e32 v55, v55, v183
	v_mul_f32_e32 v56, v56, v183
	v_mul_f32_e32 v57, v57, v183
	v_mul_f32_e32 v58, v58, v183
	v_mul_f32_e32 v59, v59, v183
	v_mul_f32_e32 v60, v60, v183
	v_mul_f32_e32 v61, v61, v183
	v_mul_f32_e32 v62, v62, v183
	v_mul_f32_e32 v63, v63, v183
	v_lshlrev_b32_e32 v181, 16, v114
	v_and_b32_e32 v114, 0xffff0000, v114
	v_mul_f32_e32 v181, v181, v183
	v_mul_f32_e32 v114, v114, v183
	v_cvt_pk_bf16_f32 v114, v181, v114
	v_lshlrev_b32_e32 v181, 16, v115
	v_and_b32_e32 v115, 0xffff0000, v115
	v_mul_f32_e32 v181, v181, v183
	v_mul_f32_e32 v115, v115, v183
	v_cvt_pk_bf16_f32 v115, v181, v115
	v_lshlrev_b32_e32 v181, 16, v116
	v_and_b32_e32 v116, 0xffff0000, v116
	v_mul_f32_e32 v181, v181, v183
	v_mul_f32_e32 v116, v116, v183
	v_cvt_pk_bf16_f32 v116, v181, v116
	v_lshlrev_b32_e32 v181, 16, v117
	v_and_b32_e32 v117, 0xffff0000, v117
	v_mul_f32_e32 v181, v181, v183
	v_mul_f32_e32 v117, v117, v183
	v_cvt_pk_bf16_f32 v117, v181, v117
	v_lshlrev_b32_e32 v181, 16, v118
	v_and_b32_e32 v118, 0xffff0000, v118
	v_mul_f32_e32 v181, v181, v183
	v_mul_f32_e32 v118, v118, v183
	v_cvt_pk_bf16_f32 v118, v181, v118
	v_lshlrev_b32_e32 v181, 16, v119
	v_and_b32_e32 v119, 0xffff0000, v119
	v_mul_f32_e32 v181, v181, v183
	v_mul_f32_e32 v119, v119, v183
	v_cvt_pk_bf16_f32 v119, v181, v119
	v_lshlrev_b32_e32 v181, 16, v120
	v_and_b32_e32 v120, 0xffff0000, v120
	v_mul_f32_e32 v181, v181, v183
	v_mul_f32_e32 v120, v120, v183
	v_cvt_pk_bf16_f32 v120, v181, v120
	v_lshlrev_b32_e32 v181, 16, v121
	v_and_b32_e32 v121, 0xffff0000, v121
	v_mul_f32_e32 v181, v181, v183
	v_mul_f32_e32 v121, v121, v183
	v_cvt_pk_bf16_f32 v121, v181, v121
	v_lshlrev_b32_e32 v181, 16, v122
	v_and_b32_e32 v122, 0xffff0000, v122
	v_mul_f32_e32 v181, v181, v183
	v_mul_f32_e32 v122, v122, v183
	v_cvt_pk_bf16_f32 v122, v181, v122
	v_lshlrev_b32_e32 v181, 16, v123
	v_and_b32_e32 v123, 0xffff0000, v123
	v_mul_f32_e32 v181, v181, v183
	v_mul_f32_e32 v123, v123, v183
	v_cvt_pk_bf16_f32 v123, v181, v123
	v_lshlrev_b32_e32 v181, 16, v124
	v_and_b32_e32 v124, 0xffff0000, v124
	v_mul_f32_e32 v181, v181, v183
	v_mul_f32_e32 v124, v124, v183
	v_cvt_pk_bf16_f32 v124, v181, v124
	v_lshlrev_b32_e32 v181, 16, v125
	v_and_b32_e32 v125, 0xffff0000, v125
	v_mul_f32_e32 v181, v181, v183
	v_mul_f32_e32 v125, v125, v183
	v_cvt_pk_bf16_f32 v125, v181, v125
	v_lshlrev_b32_e32 v181, 16, v126
	v_and_b32_e32 v126, 0xffff0000, v126
	v_mul_f32_e32 v181, v181, v183
	v_mul_f32_e32 v126, v126, v183
	v_cvt_pk_bf16_f32 v126, v181, v126
	v_lshlrev_b32_e32 v181, 16, v127
	v_and_b32_e32 v127, 0xffff0000, v127
	v_mul_f32_e32 v181, v181, v183
	v_mul_f32_e32 v127, v127, v183
	v_cvt_pk_bf16_f32 v127, v181, v127
	v_lshlrev_b32_e32 v181, 16, v128
	v_and_b32_e32 v128, 0xffff0000, v128
	v_mul_f32_e32 v181, v181, v183
	v_mul_f32_e32 v128, v128, v183
	v_cvt_pk_bf16_f32 v128, v181, v128
	v_lshlrev_b32_e32 v181, 16, v129
	v_and_b32_e32 v129, 0xffff0000, v129
	v_mul_f32_e32 v181, v181, v183
	v_mul_f32_e32 v129, v129, v183
	v_cvt_pk_bf16_f32 v129, v181, v129

.Lat_rare_8:
	v_add_u32_e32 v188, s12, v157
	v_add_u32_e32 v189, s12, v158
	v_add_u32_e32 v222, s12, v159
	v_add_u32_e32 v223, s12, v160
	s_add_i32 s16, s81, 1
	s_cmp_gt_i32 s5, s16
	s_cbranch_scc1 .Lat_noqk_3
	s_cmp_gt_i32 s5, s81
	s_cbranch_scc1 .Lat_pvonly_6
	s_waitcnt lgkmcnt(14)
	v_mfma_f32_32x32x16_bf16 v[0:15], v[224:227], v[114:117], v[0:15]
	v_exp_f32_e32 v82, v82
	v_exp_f32_e32 v83, v83
	v_mov_b32_e32 v180, 0
	ds_read_b64_tr_b16 v[224:225], v215 offset:8192
	ds_read_b64_tr_b16 v[226:227], v215 offset:10240
	s_waitcnt lgkmcnt(14)
	v_mfma_f32_32x32x16_bf16 v[16:31], v[228:231], v[114:117], v[16:31]
	v_exp_f32_e32 v84, v84
	v_exp_f32_e32 v85, v85
	v_add_f32_e32 v180, v180, v82
	v_add_f32_e32 v180, v180, v83
	ds_read_b64_tr_b16 v[228:229], v165 offset:8192
	ds_read_b64_tr_b16 v[230:231], v165 offset:10240
	s_waitcnt lgkmcnt(14)
	v_mfma_f32_32x32x16_bf16 v[32:47], v[232:235], v[114:117], v[32:47]
	v_exp_f32_e32 v86, v86
	v_exp_f32_e32 v87, v87
	v_add_f32_e32 v180, v180, v84
	v_add_f32_e32 v180, v180, v85
	ds_read_b64_tr_b16 v[232:233], v216 offset:8192
	ds_read_b64_tr_b16 v[234:235], v216 offset:10240
	s_waitcnt lgkmcnt(14)
	v_mfma_f32_32x32x16_bf16 v[48:63], v[236:239], v[114:117], v[48:63]
	v_exp_f32_e32 v88, v88
	v_exp_f32_e32 v89, v89
	v_add_f32_e32 v180, v180, v86
	v_add_f32_e32 v180, v180, v87
	ds_read_b64_tr_b16 v[236:237], v217 offset:8192
	ds_read_b64_tr_b16 v[238:239], v217 offset:10240
	s_waitcnt lgkmcnt(14)
	v_mfma_f32_32x32x16_bf16 v[0:15], v[240:243], v[118:121], v[0:15]
	v_exp_f32_e32 v90, v90
	v_exp_f32_e32 v91, v91
	v_add_f32_e32 v180, v180, v88
	v_add_f32_e32 v180, v180, v89
	v_cvt_pk_bf16_f32 v114, v82, v83
	ds_read_b64_tr_b16 v[240:241], v215 offset:12288
	ds_read_b64_tr_b16 v[242:243], v215 offset:14336
	s_waitcnt lgkmcnt(14)
	v_mfma_f32_32x32x16_bf16 v[16:31], v[130:133], v[118:121], v[16:31]
	v_exp_f32_e32 v92, v92
	v_exp_f32_e32 v93, v93
	v_add_f32_e32 v180, v180, v90
	v_add_f32_e32 v180, v180, v91
	v_cvt_pk_bf16_f32 v115, v84, v85
	ds_read_b64_tr_b16 v[130:131], v165 offset:12288
	ds_read_b64_tr_b16 v[132:133], v165 offset:14336
	s_waitcnt lgkmcnt(14)
	v_mfma_f32_32x32x16_bf16 v[32:47], v[134:137], v[118:121], v[32:47]
	v_exp_f32_e32 v94, v94
	v_exp_f32_e32 v95, v95
	v_add_f32_e32 v180, v180, v92
	v_add_f32_e32 v180, v180, v93
	v_cvt_pk_bf16_f32 v116, v86, v87
	ds_read_b64_tr_b16 v[134:135], v216 offset:12288
	ds_read_b64_tr_b16 v[136:137], v216 offset:14336
	s_waitcnt lgkmcnt(14)
	v_mfma_f32_32x32x16_bf16 v[48:63], v[184:187], v[118:121], v[48:63]
	v_exp_f32_e32 v96, v96
	v_exp_f32_e32 v97, v97
	v_add_f32_e32 v180, v180, v94
	v_add_f32_e32 v180, v180, v95
	v_cvt_pk_bf16_f32 v117, v88, v89
	ds_read_b64_tr_b16 v[184:185], v217 offset:12288
	ds_read_b64_tr_b16 v[186:187], v217 offset:14336
	s_waitcnt lgkmcnt(14)
	v_mfma_f32_32x32x16_bf16 v[0:15], v[224:227], v[122:125], v[0:15]
	v_exp_f32_e32 v98, v98
	v_exp_f32_e32 v99, v99
	v_add_f32_e32 v180, v180, v96
	v_add_f32_e32 v180, v180, v97
	v_cvt_pk_bf16_f32 v118, v90, v91
	s_waitcnt lgkmcnt(12)
	v_mfma_f32_32x32x16_bf16 v[16:31], v[228:231], v[122:125], v[16:31]
	v_exp_f32_e32 v100, v100
	v_exp_f32_e32 v101, v101
	v_add_f32_e32 v180, v180, v98
	v_add_f32_e32 v180, v180, v99
	v_cvt_pk_bf16_f32 v119, v92, v93
	s_waitcnt lgkmcnt(10)
	v_mfma_f32_32x32x16_bf16 v[32:47], v[232:235], v[122:125], v[32:47]
	v_exp_f32_e32 v102, v102
	v_exp_f32_e32 v103, v103
	v_add_f32_e32 v180, v180, v100
	v_add_f32_e32 v180, v180, v101
	v_cvt_pk_bf16_f32 v120, v94, v95
	s_waitcnt lgkmcnt(8)
	v_mfma_f32_32x32x16_bf16 v[48:63], v[236:239], v[122:125], v[48:63]
	v_exp_f32_e32 v104, v104
	v_exp_f32_e32 v105, v105
	v_add_f32_e32 v180, v180, v102
	v_add_f32_e32 v180, v180, v103
	v_cvt_pk_bf16_f32 v121, v96, v97
	ds_read_b128 v[224:227], v188
	ds_read_b128 v[228:231], v189
	ds_read_b128 v[232:235], v222
	ds_read_b128 v[236:239], v223
	s_waitcnt lgkmcnt(10)
	v_mfma_f32_32x32x16_bf16 v[0:15], v[240:243], v[126:129], v[0:15]
	v_exp_f32_e32 v106, v106
	v_exp_f32_e32 v107, v107
	v_add_f32_e32 v180, v180, v104
	v_add_f32_e32 v180, v180, v105
	v_cvt_pk_bf16_f32 v122, v98, v99
	s_waitcnt lgkmcnt(8)
	v_mfma_f32_32x32x16_bf16 v[16:31], v[130:133], v[126:129], v[16:31]
	v_exp_f32_e32 v108, v108
	v_exp_f32_e32 v109, v109
	v_add_f32_e32 v180, v180, v106
	v_add_f32_e32 v180, v180, v107
	v_cvt_pk_bf16_f32 v123, v100, v101
	s_waitcnt lgkmcnt(6)
	v_mfma_f32_32x32x16_bf16 v[32:47], v[134:137], v[126:129], v[32:47]
	v_exp_f32_e32 v110, v110
	v_exp_f32_e32 v111, v111
	v_add_f32_e32 v180, v180, v108
	v_add_f32_e32 v180, v180, v109
	v_cvt_pk_bf16_f32 v124, v102, v103
	s_waitcnt lgkmcnt(4)
	v_mfma_f32_32x32x16_bf16 v[48:63], v[184:187], v[126:129], v[48:63]
	v_exp_f32_e32 v112, v112
	v_exp_f32_e32 v113, v113
	v_add_f32_e32 v180, v180, v110
	v_add_f32_e32 v180, v180, v111
	v_cvt_pk_bf16_f32 v125, v104, v105
	s_nop 0
	v_add_f32_e32 v180, v180, v112
	v_add_f32_e32 v180, v180, v113
	v_cvt_pk_bf16_f32 v126, v106, v107
	v_cvt_pk_bf16_f32 v127, v108, v109
	v_cvt_pk_bf16_f32 v128, v110, v111
	v_cvt_pk_bf16_f32 v129, v112, v113
	v_cmp_ngt_f32_e32 vcc, s23, v180
	s_cbranch_vccz .Lat_norescale_10
	ds_bpermute_b32 v182, v214, v180
	s_waitcnt lgkmcnt(0)
	v_add_f32_e32 v182, v180, v182
	v_min_f32_e32 v182, 0x7f61b1e6, v182
	v_log_f32_e32 v182, v182
	s_nop 0
	v_floor_f32_e32 v182, v182
	v_max_f32_e32 v182, 0, v182
	v_exp_f32_e64 v183, -v182
	v_add_f32_e32 v80, v80, v182
	v_mul_f32_e32 v81, v81, v183
	v_mul_f32_e32 v180, v180, v183
	v_xor_b32_e32 v64, 0x80000000, v80
	v_mov_b32_e32 v65, v64
	v_mov_b32_e32 v66, v64
	v_mov_b32_e32 v67, v64
	v_mov_b32_e32 v68, v64
	v_mov_b32_e32 v69, v64
	v_mov_b32_e32 v70, v64
	v_mov_b32_e32 v71, v64
	v_mov_b32_e32 v72, v64
	v_mov_b32_e32 v73, v64
	v_mov_b32_e32 v74, v64
	v_mov_b32_e32 v75, v64
	v_mov_b32_e32 v76, v64
	v_mov_b32_e32 v77, v64
	v_mov_b32_e32 v78, v64
	v_mov_b32_e32 v79, v64
	v_mul_f32_e32 v82, v82, v183
	v_mul_f32_e32 v83, v83, v183
	v_mul_f32_e32 v84, v84, v183
	v_mul_f32_e32 v85, v85, v183
	v_mul_f32_e32 v86, v86, v183
	v_mul_f32_e32 v87, v87, v183
	v_mul_f32_e32 v88, v88, v183
	v_mul_f32_e32 v89, v89, v183
	v_mul_f32_e32 v90, v90, v183
	v_mul_f32_e32 v91, v91, v183
	v_mul_f32_e32 v92, v92, v183
	v_mul_f32_e32 v93, v93, v183
	v_mul_f32_e32 v94, v94, v183
	v_mul_f32_e32 v95, v95, v183
	v_mul_f32_e32 v96, v96, v183
	v_mul_f32_e32 v97, v97, v183
	v_mul_f32_e32 v98, v98, v183
	v_mul_f32_e32 v99, v99, v183
	v_mul_f32_e32 v100, v100, v183
	v_mul_f32_e32 v101, v101, v183
	v_mul_f32_e32 v102, v102, v183
	v_mul_f32_e32 v103, v103, v183
	v_mul_f32_e32 v104, v104, v183
	v_mul_f32_e32 v105, v105, v183
	v_mul_f32_e32 v106, v106, v183
	v_mul_f32_e32 v107, v107, v183
	v_mul_f32_e32 v108, v108, v183
	v_mul_f32_e32 v109, v109, v183
	v_mul_f32_e32 v110, v110, v183
	v_mul_f32_e32 v111, v111, v183
	v_mul_f32_e32 v112, v112, v183
	v_mul_f32_e32 v113, v113, v183
	v_mul_f32_e32 v0, v0, v183
	v_mul_f32_e32 v1, v1, v183
	v_mul_f32_e32 v2, v2, v183
	v_mul_f32_e32 v3, v3, v183
	v_mul_f32_e32 v4, v4, v183
	v_mul_f32_e32 v5, v5, v183
	v_mul_f32_e32 v6, v6, v183
	v_mul_f32_e32 v7, v7, v183
	v_mul_f32_e32 v8, v8, v183
	v_mul_f32_e32 v9, v9, v183
	v_mul_f32_e32 v10, v10, v183
	v_mul_f32_e32 v11, v11, v183
	v_mul_f32_e32 v12, v12, v183
	v_mul_f32_e32 v13, v13, v183
	v_mul_f32_e32 v14, v14, v183
	v_mul_f32_e32 v15, v15, v183
	v_mul_f32_e32 v16, v16, v183
	v_mul_f32_e32 v17, v17, v183
	v_mul_f32_e32 v18, v18, v183
	v_mul_f32_e32 v19, v19, v183
	v_mul_f32_e32 v20, v20, v183
	v_mul_f32_e32 v21, v21, v183
	v_mul_f32_e32 v22, v22, v183
	v_mul_f32_e32 v23, v23, v183
	v_mul_f32_e32 v24, v24, v183
	v_mul_f32_e32 v25, v25, v183
	v_mul_f32_e32 v26, v26, v183
	v_mul_f32_e32 v27, v27, v183
	v_mul_f32_e32 v28, v28, v183
	v_mul_f32_e32 v29, v29, v183
	v_mul_f32_e32 v30, v30, v183
	v_mul_f32_e32 v31, v31, v183
	v_mul_f32_e32 v32, v32, v183
	v_mul_f32_e32 v33, v33, v183
	v_mul_f32_e32 v34, v34, v183
	v_mul_f32_e32 v35, v35, v183
	v_mul_f32_e32 v36, v36, v183
	v_mul_f32_e32 v37, v37, v183
	v_mul_f32_e32 v38, v38, v183
	v_mul_f32_e32 v39, v39, v183
	v_mul_f32_e32 v40, v40, v183
	v_mul_f32_e32 v41, v41, v183
	v_mul_f32_e32 v42, v42, v183
	v_mul_f32_e32 v43, v43, v183
	v_mul_f32_e32 v44, v44, v183
	v_mul_f32_e32 v45, v45, v183
	v_mul_f32_e32 v46, v46, v183
	v_mul_f32_e32 v47, v47, v183
	v_mul_f32_e32 v48, v48, v183
	v_mul_f32_e32 v49, v49, v183
	v_mul_f32_e32 v50, v50, v183
	v_mul_f32_e32 v51, v51, v183
	v_mul_f32_e32 v52, v52, v183
	v_mul_f32_e32 v53, v53, v183
	v_mul_f32_e32 v54, v54, v183
	v_mul_f32_e32 v55, v55, v183
	v_mul_f32_e32 v56, v56, v183
	v_mul_f32_e32 v57, v57, v183
	v_mul_f32_e32 v58, v58, v183
	v_mul_f32_e32 v59, v59, v183
	v_mul_f32_e32 v60, v60, v183
	v_mul_f32_e32 v61, v61, v183
	v_mul_f32_e32 v62, v62, v183
	v_mul_f32_e32 v63, v63, v183
	v_cvt_pk_bf16_f32 v114, v82, v83
	v_cvt_pk_bf16_f32 v115, v84, v85
	v_cvt_pk_bf16_f32 v116, v86, v87
	v_cvt_pk_bf16_f32 v117, v88, v89
	v_cvt_pk_bf16_f32 v118, v90, v91
	v_cvt_pk_bf16_f32 v119, v92, v93
	v_cvt_pk_bf16_f32 v120, v94, v95
	v_cvt_pk_bf16_f32 v121, v96, v97
	v_cvt_pk_bf16_f32 v122, v98, v99
	v_cvt_pk_bf16_f32 v123, v100, v101
	v_cvt_pk_bf16_f32 v124, v102, v103
	v_cvt_pk_bf16_f32 v125, v104, v105
	v_cvt_pk_bf16_f32 v126, v106, v107
	v_cvt_pk_bf16_f32 v127, v108, v109
	v_cvt_pk_bf16_f32 v128, v110, v111
	v_cvt_pk_bf16_f32 v129, v112, v113
